# v51 plus LayerNorm panel exchanges (P6, P9): under the placement guard the per-row partial sums are written with plain stores (stay in the shared L2) instead of write-through stores; sc1 stores otherw
# baseline (speedup 1.0000x reference)
.LBB0_456:
	s_add_i32 s1, s86, -16
	s_lshr_b32 s1, s1, 3
	s_mulk_i32 s1, 0x1800
	s_lshl_b32 s0, s35, 5
	s_addk_i32 s1, 0x1800
	s_cmp_gt_i32 s86, 15
	s_cselect_b32 s6, s1, 0
	s_lshl_b32 s1, s2, 8
	v_lshrrev_b32_e32 v130, 1, v215
	s_mov_b32 s7, 0
	s_or_b32 s0, s1, s0
	v_and_or_b32 v210, v130, 24, s0
	s_lshl_b64 s[0:1], s[6:7], 2
	v_readlane_b32 s4, v242, 34
	v_readlane_b32 s5, v242, 35
	s_add_u32 s28, s4, s0
	s_addc_u32 s29, s5, s1
	s_lshl_b32 s26, s86, 8
	s_add_i32 s0, s26, s36
	v_or_b32_e32 v218, s0, v150
	s_movk_i32 s0, 0x1000
	v_ashrrev_i32_e32 v211, 31, v210
	v_add_u32_e32 v130, 0xfffff000, v218
	v_ashrrev_i32_e32 v131, 31, v218
	v_cmp_gt_i32_e32 vcc, s0, v218
	v_lshlrev_b64 v[212:213], 2, v[210:211]
	v_mov_b32_e32 v219, s59
	v_cndmask_b32_e32 v131, 0, v131, vcc
	v_cndmask_b32_e32 v130, v130, v218, vcc
	v_mov_b32_e32 v220, s57
	v_mov_b32_e32 v221, s58
	v_mov_b32_e32 v222, s56
	v_lshl_add_u64 v[146:147], s[28:29], 0, v[212:213]
	v_cndmask_b32_e32 v133, v219, v220, vcc
	v_cndmask_b32_e32 v132, v221, v222, vcc
	v_lshlrev_b64 v[130:131], 12, v[130:131]
	s_movk_i32 s1, 0x2000
	s_mov_b64 s[4:5], 0x2000
	v_lshl_add_u64 v[130:131], v[132:133], 0, v[130:131]
	v_add_co_u32_e32 v148, vcc, s1, v146
	v_lshl_add_u64 v[142:143], v[130:131], 0, v[212:213]
	s_nop 0
	v_addc_co_u32_e32 v149, vcc, 0, v147, vcc
	v_lshl_add_u64 v[146:147], v[146:147], 0, s[4:5]
	s_barrier
	s_load_dword s98, s[54:55], 0x18000
	global_load_dwordx4 v[130:133], v[142:143], off offset:16
	global_load_dwordx4 v[134:137], v[142:143], off
	global_load_dwordx4 v[138:141], v[142:143], off offset:528
	s_nop 0
	global_load_dwordx4 v[142:145], v[142:143], off offset:512
	v_and_b32_e32 v217, 63, v215
	global_load_dwordx4 v[178:181], v[148:149], off
	global_load_dwordx4 v[174:177], v[146:147], off offset:16
	global_load_dwordx4 v[170:173], v[146:147], off offset:512
	global_load_dwordx4 v[166:169], v[146:147], off offset:528
	v_or_b32_e32 v146, 16, v218
	v_add_u32_e32 v148, 0xfffff010, v218
	v_ashrrev_i32_e32 v147, 31, v146
	v_cmp_gt_i32_e32 vcc, s0, v146
	s_mov_b32 s6, 0x3f9837f0
	v_readlane_b32 s8, v242, 16
	v_cndmask_b32_e32 v147, 0, v147, vcc
	v_cndmask_b32_e32 v146, v148, v146, vcc
	v_cndmask_b32_e32 v149, v219, v220, vcc
	v_cndmask_b32_e32 v148, v221, v222, vcc
	v_lshlrev_b64 v[146:147], 12, v[146:147]
	v_lshl_add_u64 v[146:147], v[148:149], 0, v[146:147]
	v_lshl_add_u64 v[146:147], v[146:147], 0, v[212:213]
	global_load_dwordx4 v[224:227], v[146:147], off
	global_load_dwordx4 v[228:231], v[146:147], off offset:16
	global_load_dwordx4 v[232:235], v[146:147], off offset:512
	global_load_dwordx4 v[236:239], v[146:147], off offset:528
	v_or_b32_e32 v223, 32, v218
	v_lshlrev_b32_e32 v146, 6, v217
	v_readlane_b32 s20, v242, 28
	v_readlane_b32 s21, v242, 29
	v_add_u32_e32 v240, 0xfffff020, v218
	v_ashrrev_i32_e32 v241, 31, v223
	v_cmp_gt_i32_e32 vcc, s0, v223
	v_readlane_b32 s22, v242, 30
	v_readlane_b32 s23, v242, 31
	global_load_dwordx4 v[162:165], v146, s[20:21] offset:48
	s_nop 3
	global_load_dwordx4 v[182:185], v146, s[22:23] offset:48
	global_load_dwordx4 v[186:189], v146, s[20:21] offset:32
	global_load_dwordx4 v[190:193], v146, s[22:23] offset:32
	global_load_dwordx4 v[194:197], v146, s[20:21] offset:16
	global_load_dwordx4 v[198:201], v146, s[22:23] offset:16
	global_load_dwordx4 v[202:205], v146, s[20:21]
	global_load_dwordx4 v[206:209], v146, s[22:23]
	v_readlane_b32 s9, v242, 17
	v_readlane_b32 s10, v242, 18
	v_readlane_b32 s11, v242, 19
	v_readlane_b32 s12, v242, 20
	v_readlane_b32 s13, v242, 21
	v_readlane_b32 s14, v242, 22
	v_readlane_b32 s15, v242, 23
	v_readlane_b32 s16, v242, 24
	v_readlane_b32 s17, v242, 25
	v_readlane_b32 s18, v242, 26
	v_readlane_b32 s19, v242, 27
	s_waitcnt vmcnt(0)
	v_pk_mul_f32 v[130:131], v[130:131], s[6:7] op_sel_hi:[1,0]
	v_pk_mul_f32 v[138:139], v[138:139], s[6:7] op_sel_hi:[1,0]
	v_pk_mul_f32 v[140:141], v[140:141], s[6:7] op_sel_hi:[1,0]
	v_pk_mul_f32 v[136:137], v[136:137], s[6:7] op_sel_hi:[1,0]
	v_pk_mul_f32 v[134:135], v[134:135], s[6:7] op_sel_hi:[1,0]
	v_pk_fma_f32 v[146:147], v[106:107], v[166:167], v[138:139]
	v_cndmask_b32_e32 v107, 0, v241, vcc
	v_cndmask_b32_e32 v106, v240, v223, vcc
	v_pk_fma_f32 v[148:149], v[108:109], v[168:169], v[140:141]
	v_cndmask_b32_e32 v109, v219, v220, vcc
	v_cndmask_b32_e32 v108, v221, v222, vcc
	v_lshlrev_b64 v[106:107], 12, v[106:107]
	v_pk_mul_f32 v[132:133], v[132:133], s[6:7] op_sel_hi:[1,0]
	v_pk_mul_f32 v[144:145], v[144:145], s[6:7] op_sel_hi:[1,0]
	v_pk_mul_f32 v[142:143], v[142:143], s[6:7] op_sel_hi:[1,0]
	v_pk_fma_f32 v[154:155], v[122:123], v[174:175], v[130:131]
	v_lshl_add_u64 v[106:107], v[108:109], 0, v[106:107]
	v_pk_mul_f32 v[130:131], v[226:227], s[6:7] op_sel_hi:[1,0]
	v_pk_fma_f32 v[160:161], v[128:129], v[180:181], v[136:137]
	v_pk_fma_f32 v[158:159], v[126:127], v[178:179], v[134:135]
	v_pk_fma_f32 v[156:157], v[124:125], v[176:177], v[132:133]
	v_pk_fma_f32 v[152:153], v[112:113], v[172:173], v[144:145]
	v_pk_fma_f32 v[150:151], v[110:111], v[170:171], v[142:143]
	v_lshl_add_u64 v[126:127], v[106:107], 0, v[212:213]
	v_pk_mul_f32 v[132:133], v[224:225], s[6:7] op_sel_hi:[1,0]
	v_pk_fma_f32 v[144:145], v[120:121], v[180:181], v[130:131]
	v_pk_mul_f32 v[120:121], v[228:229], s[6:7] op_sel_hi:[1,0]
	global_load_dwordx4 v[106:109], v[126:127], off
	global_load_dwordx4 v[110:113], v[126:127], off offset:16
	global_load_dwordx4 v[122:125], v[126:127], off offset:528
	s_nop 0
	global_load_dwordx4 v[126:129], v[126:127], off offset:512
	v_pk_fma_f32 v[142:143], v[118:119], v[178:179], v[132:133]
	v_pk_mul_f32 v[118:119], v[230:231], s[6:7] op_sel_hi:[1,0]
	v_pk_fma_f32 v[138:139], v[114:115], v[174:175], v[120:121]
	v_pk_mul_f32 v[114:115], v[234:235], s[6:7] op_sel_hi:[1,0]
	v_pk_fma_f32 v[140:141], v[116:117], v[176:177], v[118:119]
	v_pk_mul_f32 v[116:117], v[232:233], s[6:7] op_sel_hi:[1,0]
	v_pk_fma_f32 v[136:137], v[104:105], v[172:173], v[114:115]
	v_pk_mul_f32 v[104:105], v[236:237], s[6:7] op_sel_hi:[1,0]
	v_pk_fma_f32 v[134:135], v[102:103], v[170:171], v[116:117]
	v_pk_mul_f32 v[102:103], v[238:239], s[6:7] op_sel_hi:[1,0]
	v_pk_fma_f32 v[130:131], v[98:99], v[166:167], v[104:105]
	v_or_b32_e32 v98, 48, v218
	v_pk_fma_f32 v[132:133], v[100:101], v[168:169], v[102:103]
	v_ashrrev_i32_e32 v99, 31, v98
	v_add_u32_e32 v100, 0xfffff030, v218
	v_cmp_gt_i32_e32 vcc, s0, v98
	v_add_u32_e32 v116, 0xfffff080, v218
	v_mul_f32_e32 v223, v202, v202
	v_cndmask_b32_e32 v99, 0, v99, vcc
	v_cndmask_b32_e32 v98, v100, v98, vcc
	v_cndmask_b32_e32 v101, v219, v220, vcc
	v_cndmask_b32_e32 v100, v221, v222, vcc
	v_lshlrev_b64 v[98:99], 12, v[98:99]
	v_lshl_add_u64 v[98:99], v[100:101], 0, v[98:99]
	v_lshl_add_u64 v[114:115], v[98:99], 0, v[212:213]
	global_load_dwordx4 v[98:101], v[114:115], off
	global_load_dwordx4 v[102:105], v[114:115], off offset:16
	global_load_dwordx4 v[224:227], v[114:115], off offset:512
	global_load_dwordx4 v[228:231], v[114:115], off offset:528
	v_add_u32_e32 v114, 0x80, v218
	v_ashrrev_i32_e32 v115, 31, v114
	v_cmp_gt_i32_e32 vcc, s0, v114
	v_fmac_f32_e32 v223, v203, v203
	v_fmac_f32_e32 v223, v204, v204
	v_cndmask_b32_e32 v115, 0, v115, vcc
	v_cndmask_b32_e32 v114, v116, v114, vcc
	v_cndmask_b32_e32 v117, v219, v220, vcc
	v_cndmask_b32_e32 v116, v221, v222, vcc
	v_lshlrev_b64 v[114:115], 12, v[114:115]
	v_lshl_add_u64 v[114:115], v[116:117], 0, v[114:115]
	v_lshl_add_u64 v[232:233], v[114:115], 0, v[212:213]
	v_fmac_f32_e32 v223, v205, v205
	v_fmac_f32_e32 v223, v194, v194
	v_fmac_f32_e32 v223, v195, v195
	v_fmac_f32_e32 v223, v196, v196
	v_fmac_f32_e32 v223, v197, v197
	v_fmac_f32_e32 v223, v186, v186
	v_fmac_f32_e32 v223, v187, v187
	v_fmac_f32_e32 v223, v188, v188
	v_fmac_f32_e32 v223, v189, v189
	v_fmac_f32_e32 v223, v162, v162
	v_fmac_f32_e32 v223, v163, v163
	v_fmac_f32_e32 v223, v164, v164
	v_fmac_f32_e32 v223, v165, v165
	s_waitcnt vmcnt(7)
	v_pk_mul_f32 v[108:109], v[108:109], s[6:7] op_sel_hi:[1,0]
	v_pk_mul_f32 v[106:107], v[106:107], s[6:7] op_sel_hi:[1,0]
	s_waitcnt vmcnt(6)
	v_pk_mul_f32 v[112:113], v[112:113], s[6:7] op_sel_hi:[1,0]
	v_pk_mul_f32 v[110:111], v[110:111], s[6:7] op_sel_hi:[1,0]
	s_waitcnt vmcnt(4)
	v_pk_mul_f32 v[114:115], v[128:129], s[6:7] op_sel_hi:[1,0]
	v_pk_mul_f32 v[116:117], v[126:127], s[6:7] op_sel_hi:[1,0]
	v_pk_mul_f32 v[234:235], v[124:125], s[6:7] op_sel_hi:[1,0]
	v_pk_mul_f32 v[236:237], v[122:123], s[6:7] op_sel_hi:[1,0]
	v_pk_fma_f32 v[128:129], v[96:97], v[180:181], v[108:109]
	v_pk_fma_f32 v[126:127], v[94:95], v[178:179], v[106:107]
	v_pk_fma_f32 v[124:125], v[92:93], v[176:177], v[112:113]
	v_pk_fma_f32 v[122:123], v[90:91], v[174:175], v[110:111]
	v_pk_fma_f32 v[120:121], v[88:89], v[172:173], v[114:115]
	v_pk_fma_f32 v[118:119], v[86:87], v[170:171], v[116:117]
	v_pk_fma_f32 v[116:117], v[84:85], v[168:169], v[234:235]
	v_pk_fma_f32 v[114:115], v[82:83], v[166:167], v[236:237]
	v_add_u32_e32 v106, 0x90, v218
	global_load_dwordx4 v[82:85], v[232:233], off
	global_load_dwordx4 v[86:89], v[232:233], off offset:16
	global_load_dwordx4 v[90:93], v[232:233], off offset:528
	global_load_dwordx4 v[94:97], v[232:233], off offset:512
	v_add_u32_e32 v108, 0xfffff090, v218
	v_ashrrev_i32_e32 v107, 31, v106
	v_cmp_gt_i32_e32 vcc, s0, v106
	s_waitcnt vmcnt(7)
	v_pk_mul_f32 v[100:101], v[100:101], s[6:7] op_sel_hi:[1,0]
	v_cndmask_b32_e32 v107, 0, v107, vcc
	v_cndmask_b32_e32 v106, v108, v106, vcc
	v_cndmask_b32_e32 v109, v219, v220, vcc
	v_cndmask_b32_e32 v108, v221, v222, vcc
	v_lshlrev_b64 v[106:107], 12, v[106:107]
	v_lshl_add_u64 v[106:107], v[108:109], 0, v[106:107]
	v_pk_mul_f32 v[98:99], v[98:99], s[6:7] op_sel_hi:[1,0]
	s_waitcnt vmcnt(6)
	v_pk_mul_f32 v[104:105], v[104:105], s[6:7] op_sel_hi:[1,0]
	v_pk_mul_f32 v[102:103], v[102:103], s[6:7] op_sel_hi:[1,0]
	s_waitcnt vmcnt(5)
	v_pk_mul_f32 v[226:227], v[226:227], s[6:7] op_sel_hi:[1,0]
	v_pk_mul_f32 v[224:225], v[224:225], s[6:7] op_sel_hi:[1,0]
	s_waitcnt vmcnt(4)
	v_pk_mul_f32 v[230:231], v[230:231], s[6:7] op_sel_hi:[1,0]
	v_pk_mul_f32 v[228:229], v[228:229], s[6:7] op_sel_hi:[1,0]
	v_lshl_add_u64 v[232:233], v[106:107], 0, v[212:213]
	v_pk_fma_f32 v[112:113], v[80:81], v[180:181], v[100:101]
	v_pk_fma_f32 v[110:111], v[78:79], v[178:179], v[98:99]
	v_pk_fma_f32 v[108:109], v[76:77], v[176:177], v[104:105]
	v_pk_fma_f32 v[106:107], v[74:75], v[174:175], v[102:103]
	v_pk_fma_f32 v[104:105], v[72:73], v[172:173], v[226:227]
	v_pk_fma_f32 v[102:103], v[70:71], v[170:171], v[224:225]
	v_pk_fma_f32 v[100:101], v[68:69], v[168:169], v[230:231]
	v_pk_fma_f32 v[98:99], v[66:67], v[166:167], v[228:229]
	v_add_f32_e32 v78, 0, v202
	global_load_dwordx4 v[66:69], v[232:233], off
	global_load_dwordx4 v[70:73], v[232:233], off offset:16
	global_load_dwordx4 v[224:227], v[232:233], off offset:528
	global_load_dwordx4 v[228:231], v[232:233], off offset:512
	v_add_f32_e32 v79, 0, v206
	v_fma_f32 v80, v202, v206, 0
	v_mul_f32_e32 v232, v207, v207
	v_pk_mul_f32 v[74:75], v[196:197], v[200:201]
	v_pk_mul_f32 v[76:77], v[194:195], v[198:199]
	v_add_f32_e32 v75, v203, v78
	v_add_f32_e32 v76, v207, v79
	v_fmac_f32_e32 v232, v206, v206
	v_fmac_f32_e32 v80, v203, v207
	v_add_f32_e32 v75, v204, v75
	v_add_f32_e32 v76, v208, v76
	v_fmac_f32_e32 v232, v208, v208
	v_fmac_f32_e32 v80, v204, v208
	v_mov_b32_e32 v204, v194
	v_mov_b32_e32 v208, v198
	v_add_f32_e32 v75, v205, v75
	v_add_f32_e32 v76, v209, v76
	v_pk_mul_f32 v[78:79], v[204:205], v[208:209]
	v_add_f32_e32 v75, v194, v75
	v_add_f32_e32 v76, v198, v76
	v_add_f32_e32 v79, v79, v80
	v_fmac_f32_e32 v232, v209, v209
	v_add_f32_e32 v78, v78, v79
	v_add_f32_e32 v75, v195, v75
	v_add_f32_e32 v76, v199, v76
	v_fmac_f32_e32 v232, v198, v198
	v_add_f32_e32 v75, v196, v75
	v_add_f32_e32 v196, v200, v76
	v_add_f32_e32 v76, v77, v78
	v_fmac_f32_e32 v232, v199, v199
	v_add_f32_e32 v233, v74, v76
	v_fmac_f32_e32 v232, v200, v200
	v_add_f32_e32 v200, v197, v75
	v_fmac_f32_e32 v232, v201, v201
	v_fmac_f32_e32 v232, v190, v190
	v_fmac_f32_e32 v232, v191, v191
	v_fmac_f32_e32 v232, v192, v192
	v_fmac_f32_e32 v232, v193, v193
	v_fmac_f32_e32 v232, v182, v182
	v_fmac_f32_e32 v232, v183, v183
	v_fmac_f32_e32 v232, v184, v184
	v_fmac_f32_e32 v232, v185, v185
	s_waitcnt vmcnt(7)
	v_pk_mul_f32 v[76:77], v[82:83], s[6:7] op_sel_hi:[1,0]
	s_waitcnt vmcnt(5)
	v_pk_mul_f32 v[198:199], v[90:91], s[6:7] op_sel_hi:[1,0]
	s_waitcnt vmcnt(4)
	v_pk_mul_f32 v[82:83], v[96:97], s[6:7] op_sel_hi:[1,0]
	v_pk_mul_f32 v[74:75], v[84:85], s[6:7] op_sel_hi:[1,0]
	v_pk_mul_f32 v[78:79], v[88:89], s[6:7] op_sel_hi:[1,0]
	v_pk_mul_f32 v[84:85], v[94:95], s[6:7] op_sel_hi:[1,0]
	v_pk_mul_f32 v[194:195], v[92:93], s[6:7] op_sel_hi:[1,0]
	v_pk_fma_f32 v[88:89], v[56:57], v[172:173], v[82:83]
	v_pk_fma_f32 v[82:83], v[46:47], v[166:167], v[198:199]
	v_add_u32_e32 v46, 0xa0, v218
	v_pk_mul_f32 v[80:81], v[86:87], s[6:7] op_sel_hi:[1,0]
	v_pk_fma_f32 v[86:87], v[54:55], v[170:171], v[84:85]
	v_pk_fma_f32 v[84:85], v[48:49], v[168:169], v[194:195]
	v_ashrrev_i32_e32 v47, 31, v46
	v_add_u32_e32 v48, 0xfffff0a0, v218
	v_cmp_gt_i32_e32 vcc, s0, v46
	v_pk_fma_f32 v[96:97], v[64:65], v[180:181], v[74:75]
	v_pk_fma_f32 v[94:95], v[62:63], v[178:179], v[76:77]
	v_cndmask_b32_e32 v47, 0, v47, vcc
	v_cndmask_b32_e32 v46, v48, v46, vcc
	v_cndmask_b32_e32 v49, v219, v220, vcc
	v_cndmask_b32_e32 v48, v221, v222, vcc
	v_lshlrev_b64 v[46:47], 12, v[46:47]
	v_lshl_add_u64 v[46:47], v[48:49], 0, v[46:47]
	v_pk_fma_f32 v[92:93], v[60:61], v[176:177], v[78:79]
	v_pk_fma_f32 v[90:91], v[58:59], v[174:175], v[80:81]
	v_lshl_add_u64 v[58:59], v[46:47], 0, v[212:213]
	global_load_dwordx4 v[46:49], v[58:59], off offset:16
	global_load_dwordx4 v[54:57], v[58:59], off
	global_load_dwordx4 v[202:205], v[58:59], off offset:528
	global_load_dwordx4 v[206:209], v[58:59], off offset:512
	s_waitcnt vmcnt(7)
	v_pk_mul_f32 v[58:59], v[68:69], s[6:7] op_sel_hi:[1,0]
	v_pk_mul_f32 v[60:61], v[66:67], s[6:7] op_sel_hi:[1,0]
	v_pk_fma_f32 v[80:81], v[52:53], v[180:181], v[58:59]
	s_waitcnt vmcnt(6)
	v_pk_mul_f32 v[52:53], v[70:71], s[6:7] op_sel_hi:[1,0]
	v_pk_fma_f32 v[78:79], v[50:51], v[178:179], v[60:61]
	v_pk_mul_f32 v[50:51], v[72:73], s[6:7] op_sel_hi:[1,0]
	v_pk_fma_f32 v[74:75], v[42:43], v[174:175], v[52:53]
	s_waitcnt vmcnt(4)
	v_pk_mul_f32 v[42:43], v[230:231], s[6:7] op_sel_hi:[1,0]
	v_pk_fma_f32 v[76:77], v[44:45], v[176:177], v[50:51]
	v_pk_mul_f32 v[44:45], v[228:229], s[6:7] op_sel_hi:[1,0]
	v_pk_fma_f32 v[72:73], v[40:41], v[172:173], v[42:43]
	v_pk_mul_f32 v[40:41], v[224:225], s[6:7] op_sel_hi:[1,0]
	v_pk_fma_f32 v[70:71], v[38:39], v[170:171], v[44:45]
	v_pk_mul_f32 v[38:39], v[226:227], s[6:7] op_sel_hi:[1,0]
	v_pk_fma_f32 v[66:67], v[34:35], v[166:167], v[40:41]
	v_add_u32_e32 v34, 0xb0, v218
	v_pk_fma_f32 v[68:69], v[36:37], v[168:169], v[38:39]
	v_ashrrev_i32_e32 v35, 31, v34
	v_add_u32_e32 v36, 0xfffff0b0, v218
	v_cmp_gt_i32_e32 vcc, s0, v34
	v_add_f32_e32 v42, v201, v196
	v_add_f32_e32 v53, v190, v42
	v_cndmask_b32_e32 v35, 0, v35, vcc
	v_cndmask_b32_e32 v34, v36, v34, vcc
	v_cndmask_b32_e32 v37, v219, v220, vcc
	v_cndmask_b32_e32 v36, v221, v222, vcc
	v_lshlrev_b64 v[34:35], 12, v[34:35]
	v_lshl_add_u64 v[34:35], v[36:37], 0, v[34:35]
	v_lshl_add_u64 v[50:51], v[34:35], 0, v[212:213]
	global_load_dwordx4 v[34:37], v[50:51], off offset:16
	global_load_dwordx4 v[38:41], v[50:51], off
	global_load_dwordx4 v[42:45], v[50:51], off offset:528
	global_load_dwordx4 v[218:221], v[50:51], off offset:512
	v_add_f32_e32 v52, v186, v200
	v_mov_b32_e32 v196, v186
	v_mov_b32_e32 v200, v190
	v_pk_mul_f32 v[50:51], v[196:197], v[200:201]
	s_nop 0
	v_add_f32_e32 v51, v51, v233
	v_add_f32_e32 v58, v50, v51
	v_add_f32_e32 v50, v187, v52
	v_add_f32_e32 v51, v191, v53
	v_add_f32_e32 v59, v188, v50
	v_add_f32_e32 v60, v192, v51
	v_pk_mul_f32 v[50:51], v[188:189], v[192:193]
	v_pk_mul_f32 v[52:53], v[186:187], v[190:191]
	v_mov_b32_e32 v188, v162
	v_add_f32_e32 v51, v53, v58
	v_add_f32_e32 v52, v50, v51
	v_add_f32_e32 v50, v189, v59
	v_add_f32_e32 v51, v193, v60
	v_mov_b32_e32 v192, v182
	v_add_f32_e32 v53, v162, v50
	v_add_f32_e32 v58, v182, v51
	v_pk_mul_f32 v[50:51], v[188:189], v[192:193]
	v_mul_f32_e32 v186, v165, v185
	v_add_f32_e32 v51, v51, v52
	v_add_f32_e32 v59, v50, v51
	v_add_f32_e32 v50, v163, v53
	v_add_f32_e32 v51, v183, v58
	v_add_f32_e32 v187, v164, v50
	v_add_f32_e32 v58, v184, v51
	v_pk_mul_f32 v[50:51], v[164:165], v[184:185]
	v_pk_mul_f32 v[52:53], v[162:163], v[182:183]
	v_add_f32_e32 v162, v185, v58
	v_add_f32_e32 v51, v53, v59
	v_add_f32_e32 v164, v50, v51
	v_mbcnt_lo_u32_b32 v50, -1, 0
	v_mbcnt_hi_u32_b32 v163, -1, v50
	v_and_b32_e32 v50, 64, v163
	v_add_u32_e32 v182, 64, v50
	v_xor_b32_e32 v50, 1, v163
	v_cmp_lt_i32_e32 vcc, v50, v182
	s_waitcnt vmcnt(6)
	v_pk_mul_f32 v[52:53], v[54:55], s[6:7] op_sel_hi:[1,0]
	v_cndmask_b32_e32 v183, v163, v50, vcc
	v_pk_mul_f32 v[50:51], v[56:57], s[6:7] op_sel_hi:[1,0]
	v_pk_fma_f32 v[62:63], v[30:31], v[178:179], v[52:53]
	v_pk_fma_f32 v[64:65], v[32:33], v[180:181], v[50:51]
	v_pk_mul_f32 v[32:33], v[46:47], s[6:7] op_sel_hi:[1,0]
	v_pk_mul_f32 v[30:31], v[48:49], s[6:7] op_sel_hi:[1,0]
	v_pk_fma_f32 v[58:59], v[26:27], v[174:175], v[32:33]
	s_waitcnt vmcnt(4)
	v_pk_mul_f32 v[26:27], v[208:209], s[6:7] op_sel_hi:[1,0]
	v_pk_fma_f32 v[60:61], v[28:29], v[176:177], v[30:31]
	v_pk_mul_f32 v[28:29], v[206:207], s[6:7] op_sel_hi:[1,0]
	v_pk_fma_f32 v[56:57], v[16:17], v[172:173], v[26:27]
	v_pk_mul_f32 v[16:17], v[202:203], s[6:7] op_sel_hi:[1,0]
	v_pk_fma_f32 v[54:55], v[14:15], v[170:171], v[28:29]
	v_pk_mul_f32 v[14:15], v[204:205], s[6:7] op_sel_hi:[1,0]
	v_pk_fma_f32 v[50:51], v[10:11], v[166:167], v[16:17]
	v_pk_fma_f32 v[52:53], v[12:13], v[168:169], v[14:15]
	v_pk_mul_f32 v[204:205], v[146:147], v[146:147]
	s_waitcnt vmcnt(2)
	v_pk_mul_f32 v[10:11], v[40:41], s[6:7] op_sel_hi:[1,0]
	v_pk_mul_f32 v[12:13], v[38:39], s[6:7] op_sel_hi:[1,0]
	v_pk_fma_f32 v[16:17], v[24:25], v[180:181], v[10:11]
	v_pk_mul_f32 v[10:11], v[36:37], s[6:7] op_sel_hi:[1,0]
	v_pk_fma_f32 v[14:15], v[22:23], v[178:179], v[12:13]
	v_pk_mul_f32 v[22:23], v[34:35], s[6:7] op_sel_hi:[1,0]
	v_pk_fma_f32 v[12:13], v[20:21], v[176:177], v[10:11]
	s_waitcnt vmcnt(0)
	v_pk_mul_f32 v[20:21], v[218:219], s[6:7] op_sel_hi:[1,0]
	v_pk_fma_f32 v[10:11], v[18:19], v[174:175], v[22:23]
	v_pk_mul_f32 v[18:19], v[220:221], s[6:7] op_sel_hi:[1,0]
	v_pk_fma_f32 v[6:7], v[6:7], v[170:171], v[20:21]
	v_pk_mul_f32 v[20:21], v[42:43], s[6:7] op_sel_hi:[1,0]
	v_pk_fma_f32 v[8:9], v[8:9], v[172:173], v[18:19]
	v_pk_mul_f32 v[18:19], v[44:45], s[6:7] op_sel_hi:[1,0]
	v_pk_fma_f32 v[2:3], v[2:3], v[166:167], v[20:21]
	v_lshlrev_b32_e32 v20, 2, v183
	v_pk_fma_f32 v[4:5], v[4:5], v[168:169], v[18:19]
	s_waitcnt lgkmcnt(0)
	ds_bpermute_b32 v19, v20, v223
	v_xor_b32_e32 v18, 2, v163
	v_cmp_lt_i32_e32 vcc, v18, v182
	ds_bpermute_b32 v31, v20, v162
	ds_bpermute_b32 v33, v20, v232
	v_cndmask_b32_e32 v18, v163, v18, vcc
	v_lshlrev_b32_e32 v24, 2, v18
	s_waitcnt lgkmcnt(2)
	v_add_f32_e32 v19, v223, v19
	ds_bpermute_b32 v21, v24, v19
	v_xor_b32_e32 v18, 4, v163
	v_cmp_lt_i32_e32 vcc, v18, v182
	s_waitcnt lgkmcnt(2)
	v_add_f32_e32 v31, v162, v31
	ds_bpermute_b32 v32, v24, v31
	v_cndmask_b32_e32 v18, v163, v18, vcc
	v_lshlrev_b32_e32 v25, 2, v18
	s_waitcnt lgkmcnt(1)
	v_add_f32_e32 v19, v19, v21
	ds_bpermute_b32 v21, v25, v19
	v_xor_b32_e32 v18, 8, v163
	v_cmp_lt_i32_e32 vcc, v18, v182
	s_waitcnt lgkmcnt(1)
	v_add_f32_e32 v31, v31, v32
	v_add_f32_e32 v33, v232, v33
	v_cndmask_b32_e32 v18, v163, v18, vcc
	v_lshlrev_b32_e32 v30, 2, v18
	s_waitcnt lgkmcnt(0)
	v_add_f32_e32 v19, v19, v21
	ds_bpermute_b32 v21, v30, v19
	v_xor_b32_e32 v18, 16, v163
	v_cmp_lt_i32_e32 vcc, v18, v182
	ds_bpermute_b32 v32, v25, v31
	ds_bpermute_b32 v36, v24, v33
	v_cndmask_b32_e32 v18, v163, v18, vcc
	v_lshlrev_b32_e32 v225, 2, v18
	s_waitcnt lgkmcnt(2)
	v_add_f32_e32 v19, v19, v21
	ds_bpermute_b32 v21, v225, v19
	v_xor_b32_e32 v18, 32, v163
	v_cmp_lt_i32_e32 vcc, v18, v182
	v_lshl_add_u64 v[22:23], s[20:21], 0, v[212:213]
	s_waitcnt lgkmcnt(0)
	v_add_f32_e32 v220, v19, v21
	v_cndmask_b32_e32 v18, v163, v18, vcc
	v_lshlrev_b32_e32 v224, 2, v18
	v_pk_add_f32 v[18:19], v[164:165], v[186:187]
	ds_bpermute_b32 v21, v20, v19
	ds_bpermute_b32 v20, v20, v18
	global_load_dwordx4 v[26:29], v[22:23], off offset:16
	global_load_dwordx4 v[38:41], v[22:23], off
	v_lshl_add_u64 v[34:35], s[22:23], 0, v[212:213]
	global_load_dwordx4 v[42:45], v[34:35], off offset:16
	global_load_dwordx4 v[46:49], v[34:35], off
	v_mul_f32_e32 v169, v159, v159
	s_waitcnt lgkmcnt(0)
	v_pk_add_f32 v[18:19], v[18:19], v[20:21]
	ds_bpermute_b32 v21, v24, v19
	ds_bpermute_b32 v20, v24, v18
	v_add_f32_e32 v24, v31, v32
	v_add_f32_e32 v32, v33, v36
	ds_bpermute_b32 v31, v30, v24
	ds_bpermute_b32 v33, v25, v32
	s_waitcnt lgkmcnt(2)
	v_pk_add_f32 v[18:19], v[18:19], v[20:21]
	ds_bpermute_b32 v21, v25, v19
	ds_bpermute_b32 v20, v25, v18
	s_waitcnt lgkmcnt(3)
	v_add_f32_e32 v24, v24, v31
	s_waitcnt lgkmcnt(2)
	v_add_f32_e32 v31, v32, v33
	ds_bpermute_b32 v32, v30, v31
	ds_bpermute_b32 v25, v225, v24
	s_waitcnt lgkmcnt(2)
	v_pk_add_f32 v[18:19], v[18:19], v[20:21]
	ds_bpermute_b32 v21, v30, v19
	ds_bpermute_b32 v20, v30, v18
	s_waitcnt lgkmcnt(3)
	v_add_f32_e32 v30, v31, v32
	ds_bpermute_b32 v31, v225, v30
	s_waitcnt lgkmcnt(3)
	v_add_f32_e32 v218, v24, v25
	v_fmac_f32_e32 v169, v158, v158
	s_waitcnt lgkmcnt(1)
	v_pk_add_f32 v[24:25], v[18:19], v[20:21]
	ds_bpermute_b32 v37, v225, v25
	s_waitcnt lgkmcnt(1)
	v_add_f32_e32 v222, v30, v31
	global_load_dwordx4 v[18:21], v[22:23], off offset:528
	global_load_dwordx4 v[30:33], v[22:23], off offset:512
	ds_bpermute_b32 v36, v225, v24
	v_mov_b32_e32 v166, v154
	v_mov_b32_e32 v167, v161
	v_add_f32_e32 v163, 0, v158
	v_fmac_f32_e32 v169, v160, v160
	s_waitcnt lgkmcnt(0)
	v_pk_add_f32 v[182:183], v[24:25], v[36:37]
	global_load_dwordx4 v[22:25], v[34:35], off offset:528
	s_nop 0
	global_load_dwordx4 v[34:37], v[34:35], off offset:512
	v_pk_mul_f32 v[164:165], v[166:167], v[166:167]
	v_add_f32_e32 v163, v159, v163
	v_add_f32_e32 v165, v165, v169
	v_add_f32_e32 v163, v160, v163
	v_add_f32_e32 v173, v164, v165
	v_add_f32_e32 v163, v161, v163
	v_add_f32_e32 v163, v154, v163
	v_add_f32_e32 v163, v155, v163
	v_add_f32_e32 v186, v156, v163
	v_mov_b32_e32 v187, v157
	ds_bpermute_b32 v221, v224, v220
	ds_bpermute_b32 v219, v224, v218
	ds_bpermute_b32 v223, v224, v222
	ds_bpermute_b32 v185, v224, v183
	ds_bpermute_b32 v184, v224, v182
	v_cmp_gt_u32_e32 vcc, 16, v217
	s_waitcnt vmcnt(7)
	v_mov_b32_e32 v164, v26
	s_waitcnt vmcnt(6)
	v_fma_f32 v168, v158, v38, 0
	v_mul_f32_e32 v170, v159, v39
	v_mul_f32_e32 v162, v158, v38
	v_fmac_f32_e32 v168, v159, v39
	v_mul_f32_e32 v171, v170, v170
	v_mov_b32_e32 v165, v41
	v_fmac_f32_e32 v171, v162, v162
	v_mul_f32_e32 v172, v160, v40
	v_fmac_f32_e32 v168, v160, v40
	v_pk_mul_f32 v[176:177], v[166:167], v[164:165]
	v_fmac_f32_e32 v171, v172, v172
	v_add_f32_e32 v168, v177, v168
	v_pk_mul_f32 v[166:167], v[176:177], v[176:177]
	v_pk_mul_f32 v[180:181], v[156:157], v[28:29]
	v_add_f32_e32 v167, v167, v171
	v_add_f32_e32 v171, v176, v168
	v_pk_mul_f32 v[168:169], v[154:155], v[154:155]
	v_add_f32_e32 v174, v166, v167
	v_pk_mul_f32 v[166:167], v[156:157], v[156:157]
	v_add_f32_e32 v163, v169, v173
	v_pk_mul_f32 v[178:179], v[154:155], v[26:27]
	v_add_f32_e32 v190, v166, v163
	v_pk_mul_f32 v[166:167], v[180:181], v[180:181]
	v_pk_mul_f32 v[168:169], v[178:179], v[178:179]
	v_add_f32_e32 v163, v179, v171
	v_add_f32_e32 v167, v169, v174
	v_add_f32_e32 v193, v166, v167
	s_waitcnt vmcnt(4)
	v_mov_b32_e32 v166, v46
	v_mov_b32_e32 v167, v38
	v_add_f32_e32 v192, v180, v163
	v_pk_fma_f32 v[162:163], v[162:163], v[166:167], 0 op_sel_hi:[0,1,0]
	v_mov_b32_e32 v168, v47
	v_mov_b32_e32 v169, v39
	v_pk_fma_f32 v[162:163], v[170:171], v[168:169], v[162:163] op_sel_hi:[0,1,1]
	v_mov_b32_e32 v170, v48
	v_mov_b32_e32 v171, v40
	v_pk_fma_f32 v[162:163], v[172:173], v[170:171], v[162:163] op_sel_hi:[0,1,1]
	v_mov_b32_e32 v172, v49
	v_mov_b32_e32 v173, v41
	v_pk_fma_f32 v[162:163], v[176:177], v[172:173], v[162:163] op_sel:[1,0,0]
	v_mov_b32_e32 v174, v42
	v_mov_b32_e32 v175, v26
	v_pk_fma_f32 v[162:163], v[176:177], v[174:175], v[162:163] op_sel_hi:[0,1,1]
	v_mov_b32_e32 v176, v43
	v_mov_b32_e32 v177, v27
	v_pk_fma_f32 v[162:163], v[178:179], v[176:177], v[162:163] op_sel:[1,0,0]
	v_mov_b32_e32 v178, v44
	v_mov_b32_e32 v179, v28
	v_pk_fma_f32 v[188:189], v[180:181], v[178:179], v[162:163] op_sel_hi:[0,1,1]
	v_add_f32_e32 v180, v157, v186
	v_mov_b32_e32 v186, v150
	v_add_f32_e32 v194, v150, v180
	v_pk_mul_f32 v[180:181], v[186:187], v[186:187]
	s_waitcnt vmcnt(3)
	v_pk_mul_f32 v[208:209], v[148:149], v[20:21]
	v_add_f32_e32 v181, v181, v190
	v_add_f32_e32 v195, v180, v181
	s_waitcnt vmcnt(2)
	v_mov_b32_e32 v180, v30
	v_mov_b32_e32 v181, v29
	v_pk_mul_f32 v[190:191], v[186:187], v[180:181]
	v_pk_mul_f32 v[212:213], v[208:209], v[208:209]
	v_pk_mul_f32 v[186:187], v[190:191], v[190:191]
	v_add_f32_e32 v192, v191, v192
	v_add_f32_e32 v187, v187, v193
	v_add_f32_e32 v198, v186, v187
	v_add_f32_e32 v186, v151, v194
	v_add_f32_e32 v196, v190, v192
	v_add_f32_e32 v199, v152, v186
	v_pk_mul_f32 v[186:187], v[152:153], v[152:153]
	v_pk_mul_f32 v[192:193], v[150:151], v[150:151]
	v_mov_b32_e32 v162, v45
	v_add_f32_e32 v187, v193, v195
	v_pk_mul_f32 v[194:195], v[152:153], v[32:33]
	v_pk_mul_f32 v[192:193], v[150:151], v[30:31]
	v_add_f32_e32 v200, v186, v187
	v_add_f32_e32 v201, v193, v196
	v_pk_mul_f32 v[186:187], v[194:195], v[194:195]
	v_pk_mul_f32 v[196:197], v[192:193], v[192:193]
	v_add_f32_e32 v201, v194, v201
	v_add_f32_e32 v187, v197, v198
	v_add_f32_e32 v202, v186, v187
	v_add_f32_e32 v186, v153, v199
	v_mov_b32_e32 v196, v146
	v_mov_b32_e32 v197, v153
	v_add_f32_e32 v203, v146, v186
	v_pk_mul_f32 v[186:187], v[196:197], v[196:197]
	v_mov_b32_e32 v163, v29
	v_add_f32_e32 v187, v187, v200
	v_add_f32_e32 v206, v186, v187
	v_mov_b32_e32 v186, v18
	v_mov_b32_e32 v187, v33
	v_pk_mul_f32 v[198:199], v[196:197], v[186:187]
	v_add_f32_e32 v200, v147, v203
	v_add_f32_e32 v207, v199, v201
	v_pk_mul_f32 v[196:197], v[198:199], v[198:199]
	v_add_f32_e32 v201, v205, v206
	v_add_f32_e32 v197, v197, v202
	v_add_f32_e32 v204, v198, v207
	v_mul_f32_e32 v207, v147, v19
	v_mov_b32_e32 v206, v208
	v_add_f32_e32 v205, v196, v197
	v_pk_mul_f32 v[196:197], v[206:207], v[206:207]
	v_fmac_f32_e32 v204, v147, v19
	v_add_f32_e32 v197, v197, v205
	v_mov_b32_e32 v205, v209
	v_pk_fma_f32 v[204:205], v[148:149], v[20:21], v[204:205]
	v_add_f32_e32 v197, v196, v197
	v_mov_b32_e32 v205, v213
	v_mov_b32_e32 v196, v209
	v_pk_add_f32 v[204:205], v[204:205], v[196:197]
	v_pk_fma_f32 v[196:197], v[190:191], v[162:163], v[188:189] op_sel:[1,0,0]
	s_waitcnt vmcnt(0)
	v_mov_b32_e32 v188, v34
	v_mov_b32_e32 v189, v30
	v_pk_fma_f32 v[196:197], v[190:191], v[188:189], v[196:197] op_sel_hi:[0,1,1]
	v_mov_b32_e32 v190, v35
	v_mov_b32_e32 v191, v31
	v_pk_fma_f32 v[196:197], v[192:193], v[190:191], v[196:197] op_sel:[1,0,0]
	v_mov_b32_e32 v192, v36
	v_mov_b32_e32 v193, v32
	v_pk_fma_f32 v[196:197], v[194:195], v[192:193], v[196:197] op_sel_hi:[0,1,1]
	v_mov_b32_e32 v194, v37
	v_mov_b32_e32 v195, v33
	v_pk_fma_f32 v[226:227], v[198:199], v[194:195], v[196:197] op_sel:[1,0,0]
	v_mov_b32_e32 v196, v22
	v_mov_b32_e32 v197, v18
	v_pk_fma_f32 v[226:227], v[198:199], v[196:197], v[226:227] op_sel_hi:[0,1,1]
	v_mov_b32_e32 v206, v207
	v_mov_b32_e32 v198, v23
	v_mov_b32_e32 v199, v19
	v_pk_mul_f32 v[202:203], v[148:149], v[148:149]
	v_pk_fma_f32 v[206:207], v[206:207], v[198:199], v[226:227] op_sel_hi:[0,1,1]
	v_mov_b32_e32 v226, v208
	v_mov_b32_e32 v227, v20
	v_mov_b32_e32 v228, v24
	v_mov_b32_e32 v229, v208
	v_add_f32_e32 v200, v148, v200
	v_add_f32_e32 v203, v202, v201
	v_mul_f32_e32 v201, v149, v149
	v_mov_b32_e32 v202, v149
	v_pk_fma_f32 v[206:207], v[226:227], v[228:229], v[206:207]
	v_mov_b32_e32 v226, v209
	v_mov_b32_e32 v227, v21
	v_mov_b32_e32 v208, v25
	v_pk_add_f32 v[200:201], v[202:203], v[200:201]
	v_pk_fma_f32 v[208:209], v[226:227], v[208:209], v[206:207]
	ds_bpermute_b32 v202, v225, v200
	ds_bpermute_b32 v203, v225, v201
	ds_bpermute_b32 v212, v225, v204
	ds_bpermute_b32 v213, v225, v205
	ds_bpermute_b32 v226, v225, v208
	ds_bpermute_b32 v227, v225, v209
	s_waitcnt lgkmcnt(4)
	v_pk_add_f32 v[200:201], v[200:201], v[202:203]
	ds_bpermute_b32 v202, v224, v200
	s_waitcnt lgkmcnt(3)
	v_pk_add_f32 v[206:207], v[204:205], v[212:213]
	ds_bpermute_b32 v203, v224, v201
	s_waitcnt lgkmcnt(2)
	v_pk_add_f32 v[204:205], v[208:209], v[226:227]
	ds_bpermute_b32 v212, v224, v206
	ds_bpermute_b32 v213, v224, v207
	ds_bpermute_b32 v208, v224, v204
	ds_bpermute_b32 v209, v224, v205
	s_and_saveexec_b64 s[4:5], vcc
	s_cbranch_execz .LBB0_458
	s_and_b32 s0, s3, 0x1fffff00
	v_or_b32_e32 v226, s0, v216
	v_or_b32_e32 v227, s35, v226
	v_mov_b32_e32 v226, 0
	v_mad_u64_u32 v[226:227], s[0:1], v227, 24, v[226:227]
	s_waitcnt lgkmcnt(4)
	v_pk_add_f32 v[200:201], v[200:201], v[202:203]
	s_waitcnt lgkmcnt(2)
	v_pk_add_f32 v[202:203], v[206:207], v[212:213]
	ds_write2_b64 v226, v[200:201], v[202:203] offset1:1
	s_waitcnt lgkmcnt(1)
	v_pk_add_f32 v[200:201], v[204:205], v[208:209]
	ds_write_b64 v226, v[200:201] offset:16

.LBB0_472:
	s_or_b64 exec, exec, s[4:5]
	s_waitcnt lgkmcnt(0)
	s_barrier
	v_and_b32_e32 v162, 31, v215
	s_add_u32 s18, s54, 0xf400000
	s_waitcnt lgkmcnt(5)
	v_lshl_or_b32 v166, s34, 5, v162
	s_addc_u32 s19, s55, 0
	v_cmp_gt_u32_e64 s[6:7], 32, v217
	v_add_u32_e32 v162, s26, v166
	s_and_saveexec_b64 s[8:9], s[6:7]
	s_cbranch_execz .LBB0_474
	s_movk_i32 s0, 0x60
	v_mul_lo_u32 v163, v166, s0
	v_add_u32_e32 v163, 0, v163
	s_waitcnt lgkmcnt(0)
	ds_read_b128 v[168:171], v163
	ds_read_b128 v[172:175], v163 offset:48
	ds_read_b128 v[176:179], v163 offset:16
	ds_read_b128 v[186:189], v163 offset:32
	ds_read_b128 v[190:193], v163 offset:64
	ds_read_b128 v[194:197], v163 offset:80
	s_waitcnt lgkmcnt(4)
	v_mov_b32_e32 v165, v172
	v_mov_b32_e32 v172, v169
	v_mov_b32_e32 v164, v168
	s_waitcnt lgkmcnt(1)
	v_mov_b32_e32 v181, v192
	v_mov_b32_e32 v192, v179
	v_mov_b32_e32 v180, v178
	v_pk_add_f32 v[168:169], v[172:173], v[192:193]
	v_mov_b32_e32 v172, v170
	v_mov_b32_e32 v173, v174
	v_mov_b32_e32 v178, v186
	s_waitcnt lgkmcnt(0)
	v_mov_b32_e32 v179, v194
	v_mov_b32_e32 v174, v171
	v_mov_b32_e32 v194, v187
	v_pk_add_f32 v[172:173], v[172:173], v[178:179]
	v_pk_add_f32 v[170:171], v[174:175], v[194:195]
	v_mov_b32_e32 v174, v176
	v_mov_b32_e32 v175, v190
	v_mov_b32_e32 v178, v188
	v_mov_b32_e32 v179, v196
	s_ashr_i32 s0, s2, 31
	v_pk_add_f32 v[174:175], v[174:175], v[178:179]
	v_mov_b32_e32 v190, v177
	v_mov_b32_e32 v196, v189
	v_ashrrev_i32_e32 v163, 31, v162
	v_mov_b32_e32 v178, s2
	v_mov_b32_e32 v179, s0
	v_pk_add_f32 v[164:165], v[164:165], v[180:181]
	v_pk_add_f32 v[176:177], v[190:191], v[196:197]
	v_lshl_add_u64 v[178:179], v[162:163], 2, v[178:179]
	v_pk_add_f32 v[164:165], v[164:165], v[164:165] op_sel:[0,1] op_sel_hi:[1,0]
	v_pk_add_f32 v[168:169], v[168:169], v[168:169] op_sel:[0,1] op_sel_hi:[1,0]
	v_pk_add_f32 v[172:173], v[172:173], v[172:173] op_sel:[0,1] op_sel_hi:[1,0]
	v_pk_add_f32 v[170:171], v[170:171], v[170:171] op_sel:[0,1] op_sel_hi:[1,0]
	v_pk_add_f32 v[174:175], v[174:175], v[174:175] op_sel:[0,1] op_sel_hi:[1,0]
	v_pk_add_f32 v[176:177], v[176:177], v[176:177] op_sel:[0,1] op_sel_hi:[1,0]
	v_mad_u64_u32 v[180:181], s[0:1], v178, 24, s[18:19]
	v_mad_i32_i24 v181, v179, 24, v181
	v_mov_b32_e32 v165, v168
	v_mov_b32_e32 v173, v170
	v_mov_b32_e32 v175, v176
	s_cmp_eq_u32 s98, 0
	s_cbranch_scc0 .Lx6_slow
	global_store_dwordx2 v[180:181], v[164:165], off
	global_store_dwordx2 v[180:181], v[172:173], off offset:8
	global_store_dwordx2 v[180:181], v[174:175], off offset:16
	s_branch .Lx6_join
.Lx6_slow:
	global_store_dwordx2 v[180:181], v[164:165], off sc1
	global_store_dwordx2 v[180:181], v[172:173], off offset:8 sc1
	global_store_dwordx2 v[180:181], v[174:175], off offset:16 sc1
.Lx6_join:
.LBB0_474:
	s_or_b64 exec, exec, s[8:9]
	s_waitcnt vmcnt(0)
	s_add_u32 s0, s54, 0x8000
	s_addc_u32 s1, s55, 0
	v_cmp_ne_u32_e64 s[10:11], 0, v217
	v_cmp_eq_u32_e64 s[8:9], 0, v217
	s_and_saveexec_b64 s[4:5], s[8:9]
	s_cbranch_execz .LBB0_477
	s_mov_b64 s[20:21], exec
	v_mbcnt_lo_u32_b32 v163, s20, 0
	v_mbcnt_hi_u32_b32 v163, s21, v163
	v_cmp_eq_u32_e32 vcc, 0, v163
	s_and_b64 s[22:23], exec, vcc
	s_mov_b64 exec, s[22:23]
	s_cbranch_execz .LBB0_477
	s_lshl_b32 s22, s86, 6
	s_ashr_i32 s23, s22, 31
	s_lshl_b64 s[22:23], s[22:23], 2
	s_add_u32 s22, s0, s22
	s_addc_u32 s23, s1, s23
	s_bcnt1_i32_b64 s15, s[20:21]
	v_mov_b32_e32 v163, 0
	v_mov_b32_e32 v164, s15
	global_atomic_add v163, v164, s[22:23]

.Lp9_nostraddle:
	s_lshr_b32 s99, s40, 2
	s_sub_i32 s99, s98, s99
	s_load_dword s101, s[54:55], 0x18000
	s_mov_b32 s1, 0
	s_lshl_b64 s[0:1], s[0:1], 2
	v_readlane_b32 s4, v242, 34
	v_readlane_b32 s5, v242, 35
	s_add_u32 s0, s4, s0
	s_addc_u32 s1, s5, s1
	s_lshl_b32 s18, s6, 8
	v_ashrrev_i32_e32 v123, 31, v122
	s_add_i32 s2, s99, s40
	v_lshlrev_b64 v[166:167], 2, v[122:123]
	v_or_b32_e32 v168, s2, v1
	v_lshl_add_u64 v[124:125], s[46:47], 0, v[166:167]
	v_ashrrev_i32_e32 v169, 31, v168
	s_barrier
	global_load_dwordx4 v[146:149], v[124:125], off offset:16
	global_load_dwordx4 v[154:157], v[124:125], off
	global_load_dwordx4 v[134:137], v[124:125], off offset:528
	global_load_dwordx4 v[138:141], v[124:125], off offset:512
	v_lshlrev_b64 v[124:125], 11, v[168:169]
	v_lshl_add_u64 v[124:125], s[84:85], 0, v[124:125]
	v_lshlrev_b64 v[170:171], 1, v[122:123]
	v_lshl_add_u64 v[142:143], v[124:125], 0, v[170:171]
	global_load_dwordx4 v[122:125], v[142:143], off
	global_load_dwordx4 v[174:177], v[142:143], off offset:256
	v_lshl_add_u64 v[142:143], s[0:1], 0, v[166:167]
	s_movk_i32 s2, 0x5000
	v_add_u32_e32 v178, 16, v168
	s_mov_b64 s[0:1], 0x5000
	v_add_co_u32_e32 v144, vcc, s2, v142
	v_ashrrev_i32_e32 v179, 31, v178
	s_nop 0
	v_addc_co_u32_e32 v145, vcc, 0, v143, vcc
	v_add_co_u32_e32 v240, vcc, 0xb000, v142
	s_nop 1
	v_addc_co_u32_e32 v241, vcc, 0, v143, vcc
	v_lshl_add_u64 v[142:143], v[142:143], 0, s[0:1]
	v_lshlrev_b64 v[178:179], 11, v[178:179]
	global_load_dwordx4 v[162:165], v[144:145], off
	global_load_dwordx4 v[158:161], v[142:143], off offset:16
	global_load_dwordx4 v[150:153], v[142:143], off offset:512
	s_nop 0
	global_load_dwordx4 v[142:145], v[142:143], off offset:528
	v_lshl_add_u64 v[178:179], s[84:85], 0, v[178:179]
	v_lshl_add_u64 v[182:183], v[178:179], 0, v[170:171]
	global_load_dwordx4 v[178:181], v[182:183], off
	s_nop 0
	global_load_dwordx4 v[182:185], v[182:183], off offset:256
	v_add_u32_e32 v186, 32, v168
	v_ashrrev_i32_e32 v187, 31, v186
	s_mov_b32 s0, 0x3f9837f0
	v_lshlrev_b64 v[186:187], 11, v[186:187]
	v_lshl_add_u64 v[186:187], s[84:85], 0, v[186:187]
	s_waitcnt vmcnt(0)
	v_pk_add_f32 v[108:109], v[108:109], v[148:149]
	v_pk_add_f32 v[116:117], v[116:117], v[156:157]
	v_pk_add_f32 v[114:115], v[114:115], v[154:155]
	v_pk_add_f32 v[106:107], v[106:107], v[146:147]
	v_pk_add_f32 v[100:101], v[100:101], v[140:141]
	v_pk_add_f32 v[98:99], v[98:99], v[138:139]
	v_pk_add_f32 v[84:85], v[84:85], v[136:137]
	v_lshlrev_b32_e32 v188, 16, v122
	v_and_b32_e32 v189, 0xffff0000, v122
	v_lshlrev_b32_e32 v122, 16, v123
	v_and_b32_e32 v123, 0xffff0000, v123
	v_lshlrev_b32_e32 v190, 16, v124
	v_and_b32_e32 v191, 0xffff0000, v124
	v_lshlrev_b32_e32 v124, 16, v125
	v_and_b32_e32 v125, 0xffff0000, v125
	v_lshlrev_b32_e32 v192, 16, v174
	v_and_b32_e32 v193, 0xffff0000, v174
	v_lshlrev_b32_e32 v174, 16, v175
	v_and_b32_e32 v175, 0xffff0000, v175
	v_lshlrev_b32_e32 v194, 16, v176
	v_and_b32_e32 v195, 0xffff0000, v176
	v_lshlrev_b32_e32 v176, 16, v177
	v_and_b32_e32 v177, 0xffff0000, v177
	v_pk_add_f32 v[82:83], v[82:83], v[134:135]
	v_pk_mul_f32 v[196:197], v[122:123], s[0:1] op_sel_hi:[1,0]
	v_pk_mul_f32 v[122:123], v[188:189], s[0:1] op_sel_hi:[1,0]
	v_pk_mul_f32 v[188:189], v[190:191], s[0:1] op_sel_hi:[1,0]
	v_pk_mul_f32 v[190:191], v[124:125], s[0:1] op_sel_hi:[1,0]
	v_pk_mul_f32 v[192:193], v[192:193], s[0:1] op_sel_hi:[1,0]
	v_pk_mul_f32 v[174:175], v[174:175], s[0:1] op_sel_hi:[1,0]
	v_pk_mul_f32 v[194:195], v[194:195], s[0:1] op_sel_hi:[1,0]
	v_pk_mul_f32 v[176:177], v[176:177], s[0:1] op_sel_hi:[1,0]
	v_pk_fma_f32 v[122:123], v[162:163], v[114:115], v[122:123]
	v_pk_fma_f32 v[124:125], v[164:165], v[116:117], v[196:197]
	v_pk_fma_f32 v[116:117], v[160:161], v[108:109], v[190:191]
	v_pk_fma_f32 v[114:115], v[158:159], v[106:107], v[188:189]
	v_pk_fma_f32 v[108:109], v[152:153], v[100:101], v[174:175]
	v_pk_fma_f32 v[106:107], v[150:151], v[98:99], v[192:193]
	v_pk_fma_f32 v[100:101], v[144:145], v[84:85], v[176:177]
	v_pk_fma_f32 v[98:99], v[142:143], v[82:83], v[194:195]
	v_lshl_add_u64 v[82:83], v[186:187], 0, v[170:171]
	s_cmp_eq_u32 s100, 1
	s_cbranch_scc0 .Lp9_gate_1
	global_load_dwordx4 v[162:165], v[240:241], off
	global_load_dwordx4 v[158:161], v[240:241], off offset:16
	global_load_dwordx4 v[150:153], v[240:241], off offset:512
	global_load_dwordx4 v[142:145], v[240:241], off offset:528
	s_waitcnt vmcnt(0)

.Lp9_gate_6:
	global_load_dwordx4 v[130:133], v[168:169], off
	s_nop 0
	global_load_dwordx4 v[168:171], v[168:169], off offset:256
	s_waitcnt vmcnt(2)
	v_lshlrev_b32_e32 v178, 16, v182
	v_and_b32_e32 v179, 0xffff0000, v182
	v_pk_mul_f32 v[178:179], v[178:179], s[0:1] op_sel_hi:[1,0]
	v_lshlrev_b32_e32 v180, 16, v183
	v_pk_fma_f32 v[34:35], v[162:163], v[34:35], v[178:179]
	v_lshlrev_b32_e32 v178, 16, v184
	v_and_b32_e32 v179, 0xffff0000, v184
	v_pk_mul_f32 v[178:179], v[178:179], s[0:1] op_sel_hi:[1,0]
	v_and_b32_e32 v181, 0xffff0000, v183
	v_pk_fma_f32 v[26:27], v[158:159], v[26:27], v[178:179]
	v_lshlrev_b32_e32 v178, 16, v174
	v_and_b32_e32 v179, 0xffff0000, v174
	v_lshlrev_b32_e32 v174, 16, v175
	v_and_b32_e32 v175, 0xffff0000, v175
	v_pk_mul_f32 v[174:175], v[174:175], s[0:1] op_sel_hi:[1,0]
	v_pk_mul_f32 v[180:181], v[180:181], s[0:1] op_sel_hi:[1,0]
	v_pk_fma_f32 v[24:25], v[152:153], v[24:25], v[174:175]
	v_lshlrev_b32_e32 v174, 16, v176
	v_and_b32_e32 v175, 0xffff0000, v176
	v_pk_mul_f32 v[174:175], v[174:175], s[0:1] op_sel_hi:[1,0]
	v_pk_fma_f32 v[36:37], v[164:165], v[36:37], v[180:181]
	v_pk_fma_f32 v[14:15], v[142:143], v[14:15], v[174:175]
	v_lshlrev_b32_e32 v180, 16, v185
	v_and_b32_e32 v181, 0xffff0000, v185
	v_lshlrev_b32_e32 v176, 16, v177
	v_and_b32_e32 v177, 0xffff0000, v177
	v_pk_mul_f32 v[180:181], v[180:181], s[0:1] op_sel_hi:[1,0]
	v_pk_mul_f32 v[178:179], v[178:179], s[0:1] op_sel_hi:[1,0]
	v_pk_mul_f32 v[176:177], v[176:177], s[0:1] op_sel_hi:[1,0]
	v_pk_fma_f32 v[28:29], v[160:161], v[28:29], v[180:181]
	v_pk_fma_f32 v[22:23], v[150:151], v[22:23], v[178:179]
	v_pk_fma_f32 v[16:17], v[144:145], v[16:17], v[176:177]
	s_waitcnt vmcnt(1)
	v_lshlrev_b32_e32 v174, 16, v130
	v_and_b32_e32 v175, 0xffff0000, v130
	v_lshlrev_b32_e32 v130, 16, v131
	v_and_b32_e32 v131, 0xffff0000, v131
	v_pk_mul_f32 v[130:131], v[130:131], s[0:1] op_sel_hi:[1,0]
	v_pk_mul_f32 v[174:175], v[174:175], s[0:1] op_sel_hi:[1,0]
	v_pk_fma_f32 v[20:21], v[164:165], v[20:21], v[130:131]
	v_lshlrev_b32_e32 v130, 16, v132
	v_and_b32_e32 v131, 0xffff0000, v132
	v_lshlrev_b32_e32 v132, 16, v133
	v_and_b32_e32 v133, 0xffff0000, v133
	v_pk_mul_f32 v[130:131], v[130:131], s[0:1] op_sel_hi:[1,0]
	v_pk_mul_f32 v[132:133], v[132:133], s[0:1] op_sel_hi:[1,0]
	v_pk_fma_f32 v[10:11], v[158:159], v[10:11], v[130:131]
	v_pk_fma_f32 v[12:13], v[160:161], v[12:13], v[132:133]
	s_waitcnt vmcnt(0)
	v_lshlrev_b32_e32 v130, 16, v168
	v_and_b32_e32 v131, 0xffff0000, v168
	v_lshlrev_b32_e32 v132, 16, v169
	v_and_b32_e32 v133, 0xffff0000, v169
	v_pk_mul_f32 v[130:131], v[130:131], s[0:1] op_sel_hi:[1,0]
	v_pk_mul_f32 v[132:133], v[132:133], s[0:1] op_sel_hi:[1,0]
	v_pk_fma_f32 v[6:7], v[150:151], v[6:7], v[130:131]
	v_pk_fma_f32 v[8:9], v[152:153], v[8:9], v[132:133]
	v_lshlrev_b32_e32 v130, 16, v170
	v_and_b32_e32 v131, 0xffff0000, v170
	v_lshlrev_b32_e32 v132, 16, v171
	v_and_b32_e32 v133, 0xffff0000, v171
	v_pk_mul_f32 v[130:131], v[130:131], s[0:1] op_sel_hi:[1,0]
	v_pk_mul_f32 v[132:133], v[132:133], s[0:1] op_sel_hi:[1,0]
	v_pk_fma_f32 v[18:19], v[162:163], v[18:19], v[174:175]
	v_pk_fma_f32 v[4:5], v[144:145], v[4:5], v[132:133]
	v_pk_fma_f32 v[2:3], v[142:143], v[2:3], v[130:131]
	v_lshl_add_u64 v[142:143], s[50:51], 0, v[166:167]
	global_load_dwordx4 v[146:149], v[134:135], off offset:16
	global_load_dwordx4 v[154:157], v[134:135], off
	global_load_dwordx4 v[130:133], v[134:135], off offset:528
	global_load_dwordx4 v[138:141], v[134:135], off offset:512
	global_load_dwordx4 v[150:153], v[142:143], off offset:16
	global_load_dwordx4 v[158:161], v[142:143], off
	s_nop 0
	global_load_dwordx4 v[134:137], v[142:143], off offset:528
	s_nop 0
	global_load_dwordx4 v[142:145], v[142:143], off offset:512
	v_mbcnt_lo_u32_b32 v162, -1, 0
	v_mbcnt_hi_u32_b32 v163, -1, v162
	v_and_b32_e32 v164, 64, v163
	v_add_u32_e32 v173, 64, v164
	v_mov_b32_e32 v164, v123
	v_mov_b32_e32 v165, v124
	v_mov_b32_e32 v168, v122
	v_mov_b32_e32 v169, v125
	v_pk_add_f32 v[164:165], v[164:165], v[168:169]
	v_mov_b32_e32 v168, v115
	v_mov_b32_e32 v169, v116
	v_mov_b32_e32 v170, v114
	v_mov_b32_e32 v171, v117
	v_pk_add_f32 v[168:169], v[168:169], v[170:171]
	v_add_f32_e32 v164, v164, v165
	v_pk_add_f32 v[168:169], v[168:169], v[168:169] op_sel_hi:[0,1]
	v_xor_b32_e32 v162, 16, v163
	v_add_f32_e32 v165, 0, v164
	v_add_f32_e32 v171, v106, v107
	v_add_f32_e32 v175, v108, v109
	v_mov_b32_e32 v170, v98
	v_mov_b32_e32 v174, v99
	v_mov_b32_e32 v168, v100
	v_mov_b32_e32 v164, v101
	v_cmp_lt_i32_e32 vcc, v162, v173
	v_pk_add_f32 v[170:171], v[170:171], v[174:175]
	v_pk_add_f32 v[164:165], v[168:169], v[164:165]
	v_cndmask_b32_e32 v162, v163, v162, vcc
	v_pk_add_f32 v[164:165], v[170:171], v[164:165]
	v_lshlrev_b32_e32 v162, 2, v162
	v_add_f32_e32 v165, v164, v165
	s_waitcnt lgkmcnt(0)
	ds_bpermute_b32 v168, v162, v165
	v_xor_b32_e32 v164, 32, v163
	v_cmp_lt_i32_e32 vcc, v164, v173
	s_lshl_b32 s0, s7, 3
	s_add_i32 s2, s0, 0
	v_cndmask_b32_e32 v163, v163, v164, vcc
	v_lshlrev_b32_e32 v164, 2, v163
	s_waitcnt lgkmcnt(0)
	v_add_f32_e32 v163, v165, v168
	ds_bpermute_b32 v165, v164, v163
	s_waitcnt lgkmcnt(0)
	v_add_f32_e32 v165, v163, v165
	v_fmamk_f32 v168, v165, 0xbc800000, v125
	v_fmamk_f32 v170, v165, 0xbc800000, v123
	v_fmamk_f32 v163, v165, 0xbc800000, v124
	v_fmamk_f32 v169, v165, 0xbc800000, v122
	v_mul_f32_e32 v170, v170, v170
	v_mul_f32_e32 v168, v168, v168
	v_fmac_f32_e32 v170, v169, v169
	v_fmac_f32_e32 v168, v163, v163
	v_fmamk_f32 v169, v165, 0xbc800000, v117
	v_fmamk_f32 v171, v165, 0xbc800000, v115
	v_add_f32_e32 v163, v170, v168
	v_fmamk_f32 v168, v165, 0xbc800000, v116
	v_fmamk_f32 v170, v165, 0xbc800000, v114
	v_mul_f32_e32 v171, v171, v171
	v_mul_f32_e32 v169, v169, v169
	v_fmac_f32_e32 v171, v170, v170
	v_fmac_f32_e32 v169, v168, v168
	v_add_f32_e32 v168, v171, v169
	v_fmamk_f32 v169, v165, 0xbc800000, v109
	v_fmamk_f32 v171, v165, 0xbc800000, v107
	v_add_f32_e32 v163, v163, v168
	v_fmamk_f32 v168, v165, 0xbc800000, v108
	v_fmamk_f32 v170, v165, 0xbc800000, v106
	v_mul_f32_e32 v171, v171, v171
	v_mul_f32_e32 v169, v169, v169
	v_fmac_f32_e32 v171, v170, v170
	v_fmac_f32_e32 v169, v168, v168
	v_add_f32_e32 v168, v171, v169
	v_fmamk_f32 v169, v165, 0xbc800000, v101
	v_fmamk_f32 v171, v165, 0xbc800000, v99
	v_add_f32_e32 v163, v168, v163
	v_fmamk_f32 v168, v165, 0xbc800000, v100
	v_fmamk_f32 v170, v165, 0xbc800000, v98
	v_mul_f32_e32 v171, v171, v171
	v_mul_f32_e32 v169, v169, v169
	v_fmac_f32_e32 v171, v170, v170
	v_fmac_f32_e32 v169, v168, v168
	v_add_f32_e32 v168, v171, v169
	v_add_f32_e32 v163, v168, v163
	ds_bpermute_b32 v168, v162, v163
	s_waitcnt lgkmcnt(0)
	v_add_f32_e32 v168, v163, v168
	ds_bpermute_b32 v169, v164, v168
	v_and_b32_e32 v163, 63, v0
	v_cmp_gt_u32_e32 vcc, 16, v163
	s_and_saveexec_b64 s[0:1], vcc
	s_cbranch_execz .LBB0_656
	s_lshl_b32 s4, s11, 11
	s_add_i32 s4, s2, s4
	v_mul_f32_e32 v170, 0x3c800000, v165
	v_lshl_add_u32 v165, v1, 5, s4
	s_waitcnt lgkmcnt(0)
	v_add_f32_e32 v171, v168, v169
	ds_write_b64 v165, v[170:171]

.LBB0_670:
	s_or_b64 exec, exec, s[0:1]
	v_and_b32_e32 v0, 31, v0
	s_waitcnt lgkmcnt(0)
	s_barrier
	s_waitcnt lgkmcnt(0)
	v_lshl_or_b32 v164, s3, 5, v0
	s_add_u32 s8, s54, 0xf580000
	v_add_u32_e32 v0, s18, v164
	s_addc_u32 s9, s55, 0
	v_cmp_gt_u32_e64 s[0:1], 32, v163
	v_ashrrev_i32_e32 v1, 31, v0
	s_and_saveexec_b64 s[2:3], s[0:1]
	s_cbranch_execz .LBB0_672
	v_lshl_add_u32 v162, v164, 5, 0
	ds_read_b128 v[168:171], v162
	ds_read_b128 v[174:177], v162 offset:16
	s_ashr_i32 s11, s10, 31
	s_waitcnt lgkmcnt(1)
	v_add_f32_e32 v162, v168, v170
	s_waitcnt lgkmcnt(0)
	v_add_f32_e32 v162, v162, v174
	v_add_f32_e32 v162, v162, v176
	v_fmamk_f32 v165, v162, 0xbe800000, v168
	v_fmac_f32_e32 v170, 0xbe800000, v162
	v_fmamk_f32 v168, v162, 0xbe800000, v174
	v_fmac_f32_e32 v176, 0xbe800000, v162
	v_mul_f32_e32 v181, v165, v165
	v_mul_f32_e32 v183, v170, v170
	v_mul_f32_e32 v185, v168, v168
	v_mul_f32_e32 v187, v176, v176
	v_mov_b32_e32 v180, v169
	v_mov_b32_e32 v182, v171
	v_mov_b32_e32 v184, v175
	v_mov_b32_e32 v186, v177
	v_pk_add_f32 v[168:169], v[180:181], v[182:183]
	v_pk_add_f32 v[170:171], v[184:185], v[186:187]
	v_mul_f32_e32 v178, 0x3e800000, v162
	v_pk_add_f32 v[168:169], v[168:169], v[170:171]
	s_nop 0
	v_fmamk_f32 v179, v169, 0x42800000, v168
	v_lshlrev_b64 v[168:169], 5, v[0:1]
	v_lshl_add_u64 v[168:169], s[8:9], 0, v[168:169]
	v_lshl_add_u64 v[168:169], s[10:11], 3, v[168:169]
	s_cmp_eq_u32 s101, 0
	s_cbranch_scc0 .Lx9_slow
	global_store_dwordx2 v[168:169], v[178:179], off
	s_branch .Lx9_join
.Lx9_slow:
	global_store_dwordx2 v[168:169], v[178:179], off sc1
.Lx9_join:
.LBB0_672:
	s_or_b64 exec, exec, s[2:3]
	s_waitcnt vmcnt(0)
	s_add_u32 s7, s54, 0x10000
	s_addc_u32 s14, s55, 0
	v_cmp_ne_u32_e64 s[4:5], 0, v163
	v_cmp_eq_u32_e64 s[2:3], 0, v163
	s_and_saveexec_b64 s[10:11], s[2:3]
	s_cbranch_execz .LBB0_675
	s_mov_b64 s[12:13], exec
	v_mbcnt_lo_u32_b32 v162, s12, 0
	v_mbcnt_hi_u32_b32 v162, s13, v162
	v_cmp_eq_u32_e32 vcc, 0, v162
	s_and_b64 s[16:17], exec, vcc
	s_mov_b64 exec, s[16:17]
	s_cbranch_execz .LBB0_675
	s_lshl_b32 s16, s6, 6
	s_ashr_i32 s17, s16, 31
	s_lshl_b64 s[16:17], s[16:17], 2
	s_add_u32 s16, s7, s16
	s_addc_u32 s17, s14, s17
	s_bcnt1_i32_b64 s12, s[12:13]
	v_mov_b32_e32 v162, 0
	v_mov_b32_e32 v163, s12
	global_atomic_add v162, v163, s[16:17]
